# nt on P4's f32 k/v module-output stores (never read again by the kernel)
# speedup vs baseline: 1.0478x; 1.0075x over previous
; #define EM_PK8(a, b) ((u32x4){cvt_pk_bf16((a)[0], (a)[1]), cvt_pk_bf16((a)[2], (a)[3]), cvt_pk_bf16((b)[0], (b)[1]), cvt_pk_bf16((b)[2], (b)[3])})
;     __device__ __forceinline__ void operator()(const f32x4 (&acc)[2][2][4][2], const Unit& u, int wr, int wc, int fr, int fq) const {
;     ...
;                 for (int bj = 0; bj < 2; ++bj) { const int col = col0 + bj * HALF; const f32x4 v0 = acc[ai][bj][m][0], v1 = acc[ai][bj][m][1];
;                     if (samp || pn == 14) { float* pp = P + (size_t)row * 3840 + col; *(f32x4*)pp = v0; *(f32x4*)(pp + 4) = v1; }
;                     else if (pn >= 6) *(u32x4*)(PB + (size_t)row * 2048 + (col - 1536)) = EM_PK8(v0, v1);
;                     if (pn < 2) { if (!samp) { const f32x4 q0 = v0 * c2, q1 = v1 * c2; *(u32x4*)(Qb + (size_t)row * 512 + col) = EM_PK8(q0, q1); } }
;                     else if (pn < 4) { const int c = col - 512; float* ko = (samp ? out + o_ks + (size_t)(row - mp) * 512 : out + o_kp + (size_t)row * 512) + c; *(f32x4*)ko = v0; *(f32x4*)(ko + 4) = v1;
;                         if (!samp) *(u32x4*)(Kb + (size_t)row * 512 + c) = EM_PK8(v0, v1); }
;                     else if (pn < 6) { const int c = col - 1024; float* vo = (samp ? out + o_vs + (size_t)(row - mp) * 512 : out + o_vp + (size_t)row * 512) + c; *(f32x4*)vo = v0; *(f32x4*)(vo + 4) = v1;
;                         if (!samp) *(u32x4*)(Vb + (size_t)row * 512 + c) = EM_PK8(v0, v1); }
.Lp4epi_K:
	v_readlane_b32 s98, v244, 22
	v_readlane_b32 s99, v244, 23
	v_lshl_add_u32 v254, s6, 8, v1
	v_lshl_or_b32 v255, s8, 8, v163
	v_lshlrev_b32_e32 v252, 11, v254
	v_lshl_add_u32 v252, v255, 2, v252
	v_add_u32_e32 v252, 0xfffff800, v252
	v_lshlrev_b32_e32 v253, 10, v254
	v_lshl_add_u32 v253, v255, 1, v253
	v_add_u32_e32 v253, 0xfffffc00, v253
	v_mov_b32_e32 v254, v252
	v_mov_b32_e32 v255, v253
	global_store_dwordx4 v254, v[126:129], s[74:75] nt
	global_store_dwordx4 v254, v[122:125], s[74:75] offset:16 nt
	v_cvt_pk_bf16_f32 v246, v126, v127
	v_cvt_pk_bf16_f32 v247, v128, v129
	v_cvt_pk_bf16_f32 v248, v122, v123
	v_cvt_pk_bf16_f32 v249, v124, v125
	global_store_dwordx4 v255, v[246:249], s[98:99]
	s_nop 1
	global_store_dwordx4 v254, v[118:121], s[74:75] offset:512 nt
	global_store_dwordx4 v254, v[114:117], s[74:75] offset:528 nt
	v_cvt_pk_bf16_f32 v246, v118, v119
	v_cvt_pk_bf16_f32 v247, v120, v121
	v_cvt_pk_bf16_f32 v248, v114, v115
	v_cvt_pk_bf16_f32 v249, v116, v117
	global_store_dwordx4 v255, v[246:249], s[98:99] offset:256
	s_nop 1
	v_add_u32_e32 v254, 0x8000, v252
	v_add_u32_e32 v255, 0x4000, v253
	global_store_dwordx4 v254, v[110:113], s[74:75] nt
	global_store_dwordx4 v254, v[106:109], s[74:75] offset:16 nt
	v_cvt_pk_bf16_f32 v246, v110, v111
	v_cvt_pk_bf16_f32 v247, v112, v113
	v_cvt_pk_bf16_f32 v248, v106, v107
	v_cvt_pk_bf16_f32 v249, v108, v109
	global_store_dwordx4 v255, v[246:249], s[98:99]
	s_nop 1
	global_store_dwordx4 v254, v[102:105], s[74:75] offset:512 nt
	global_store_dwordx4 v254, v[98:101], s[74:75] offset:528 nt
	v_cvt_pk_bf16_f32 v246, v102, v103
	v_cvt_pk_bf16_f32 v247, v104, v105
	v_cvt_pk_bf16_f32 v248, v98, v99
	v_cvt_pk_bf16_f32 v249, v100, v101
	global_store_dwordx4 v255, v[246:249], s[98:99] offset:256
	s_nop 1
	v_add_u32_e32 v254, 0x10000, v252
	v_add_u32_e32 v255, 0x8000, v253
	global_store_dwordx4 v254, v[94:97], s[74:75] nt
	global_store_dwordx4 v254, v[90:93], s[74:75] offset:16 nt
	v_cvt_pk_bf16_f32 v246, v94, v95
	v_cvt_pk_bf16_f32 v247, v96, v97
	v_cvt_pk_bf16_f32 v248, v90, v91
	v_cvt_pk_bf16_f32 v249, v92, v93
	global_store_dwordx4 v255, v[246:249], s[98:99]
	s_nop 1
	global_store_dwordx4 v254, v[86:89], s[74:75] offset:512 nt
	global_store_dwordx4 v254, v[82:85], s[74:75] offset:528 nt
	v_cvt_pk_bf16_f32 v246, v86, v87
	v_cvt_pk_bf16_f32 v247, v88, v89
	v_cvt_pk_bf16_f32 v248, v82, v83
	v_cvt_pk_bf16_f32 v249, v84, v85
	global_store_dwordx4 v255, v[246:249], s[98:99] offset:256
	s_nop 1
	v_add_u32_e32 v254, 0x18000, v252
	v_add_u32_e32 v255, 0xc000, v253
	global_store_dwordx4 v254, v[78:81], s[74:75] nt
	global_store_dwordx4 v254, v[74:77], s[74:75] offset:16 nt
	v_cvt_pk_bf16_f32 v246, v78, v79
	v_cvt_pk_bf16_f32 v247, v80, v81
	v_cvt_pk_bf16_f32 v248, v74, v75
	v_cvt_pk_bf16_f32 v249, v76, v77
	global_store_dwordx4 v255, v[246:249], s[98:99]
	s_nop 1
	global_store_dwordx4 v254, v[70:73], s[74:75] offset:512 nt
	global_store_dwordx4 v254, v[66:69], s[74:75] offset:528 nt
	v_cvt_pk_bf16_f32 v246, v70, v71
	v_cvt_pk_bf16_f32 v247, v72, v73
	v_cvt_pk_bf16_f32 v248, v66, v67
	v_cvt_pk_bf16_f32 v249, v68, v69
	global_store_dwordx4 v255, v[246:249], s[98:99] offset:256
	s_nop 1
	v_add_u32_e32 v254, 0x40000, v252
	v_add_u32_e32 v255, 0x20000, v253
	global_store_dwordx4 v254, v[62:65], s[74:75] nt
	global_store_dwordx4 v254, v[58:61], s[74:75] offset:16 nt
	v_cvt_pk_bf16_f32 v246, v62, v63
	v_cvt_pk_bf16_f32 v247, v64, v65
	v_cvt_pk_bf16_f32 v248, v58, v59
	v_cvt_pk_bf16_f32 v249, v60, v61
	global_store_dwordx4 v255, v[246:249], s[98:99]
	s_nop 1
	global_store_dwordx4 v254, v[54:57], s[74:75] offset:512 nt
	global_store_dwordx4 v254, v[50:53], s[74:75] offset:528 nt
	v_cvt_pk_bf16_f32 v246, v54, v55
	v_cvt_pk_bf16_f32 v247, v56, v57
	v_cvt_pk_bf16_f32 v248, v50, v51
	v_cvt_pk_bf16_f32 v249, v52, v53
	global_store_dwordx4 v255, v[246:249], s[98:99] offset:256
	s_nop 1
	v_add_u32_e32 v254, 0x48000, v252
	v_add_u32_e32 v255, 0x24000, v253
	global_store_dwordx4 v254, v[46:49], s[74:75] nt
	global_store_dwordx4 v254, v[42:45], s[74:75] offset:16 nt
	v_cvt_pk_bf16_f32 v246, v46, v47
	v_cvt_pk_bf16_f32 v247, v48, v49
	v_cvt_pk_bf16_f32 v248, v42, v43
	v_cvt_pk_bf16_f32 v249, v44, v45
	global_store_dwordx4 v255, v[246:249], s[98:99]
	s_nop 1
	global_store_dwordx4 v254, v[38:41], s[74:75] offset:512 nt
	global_store_dwordx4 v254, v[34:37], s[74:75] offset:528 nt
	v_cvt_pk_bf16_f32 v246, v38, v39
	v_cvt_pk_bf16_f32 v247, v40, v41
	v_cvt_pk_bf16_f32 v248, v34, v35
	v_cvt_pk_bf16_f32 v249, v36, v37
	global_store_dwordx4 v255, v[246:249], s[98:99] offset:256
	s_nop 1
	v_add_u32_e32 v254, 0x50000, v252
	v_add_u32_e32 v255, 0x28000, v253
	global_store_dwordx4 v254, v[30:33], s[74:75] nt
	global_store_dwordx4 v254, v[26:29], s[74:75] offset:16 nt
	v_cvt_pk_bf16_f32 v246, v30, v31
	v_cvt_pk_bf16_f32 v247, v32, v33
	v_cvt_pk_bf16_f32 v248, v26, v27
	v_cvt_pk_bf16_f32 v249, v28, v29
	global_store_dwordx4 v255, v[246:249], s[98:99]
	s_nop 1
	global_store_dwordx4 v254, v[22:25], s[74:75] offset:512 nt
	global_store_dwordx4 v254, v[18:21], s[74:75] offset:528 nt
	v_cvt_pk_bf16_f32 v246, v22, v23
	v_cvt_pk_bf16_f32 v247, v24, v25
	v_cvt_pk_bf16_f32 v248, v18, v19
	v_cvt_pk_bf16_f32 v249, v20, v21
	global_store_dwordx4 v255, v[246:249], s[98:99] offset:256
	s_nop 1
	v_add_u32_e32 v254, 0x58000, v252
	v_add_u32_e32 v255, 0x2c000, v253
	global_store_dwordx4 v254, v[14:17], s[74:75] nt
	global_store_dwordx4 v254, v[10:13], s[74:75] offset:16 nt
	v_cvt_pk_bf16_f32 v246, v14, v15
	v_cvt_pk_bf16_f32 v247, v16, v17
	v_cvt_pk_bf16_f32 v248, v10, v11
	v_cvt_pk_bf16_f32 v249, v12, v13
	global_store_dwordx4 v255, v[246:249], s[98:99]
	s_nop 1
	global_store_dwordx4 v254, v[6:9], s[74:75] offset:512 nt
	global_store_dwordx4 v254, v[2:5], s[74:75] offset:528 nt
	v_cvt_pk_bf16_f32 v246, v6, v7
	v_cvt_pk_bf16_f32 v247, v8, v9
	v_cvt_pk_bf16_f32 v248, v2, v3
	v_cvt_pk_bf16_f32 v249, v4, v5
	global_store_dwordx4 v255, v[246:249], s[98:99] offset:256
	s_nop 1
	s_branch .LBB0_945
; #define EM_PK8(a, b) ((u32x4){cvt_pk_bf16((a)[0], (a)[1]), cvt_pk_bf16((a)[2], (a)[3]), cvt_pk_bf16((b)[0], (b)[1]), cvt_pk_bf16((b)[2], (b)[3])})
;     __device__ __forceinline__ void operator()(const f32x4 (&acc)[2][2][4][2], const Unit& u, int wr, int wc, int fr, int fq) const {
;     ...
;                 for (int bj = 0; bj < 2; ++bj) { const int col = col0 + bj * HALF; const f32x4 v0 = acc[ai][bj][m][0], v1 = acc[ai][bj][m][1];
;                     if (samp || pn == 14) { float* pp = P + (size_t)row * 3840 + col; *(f32x4*)pp = v0; *(f32x4*)(pp + 4) = v1; }
;                     else if (pn >= 6) *(u32x4*)(PB + (size_t)row * 2048 + (col - 1536)) = EM_PK8(v0, v1);
;                     if (pn < 2) { if (!samp) { const f32x4 q0 = v0 * c2, q1 = v1 * c2; *(u32x4*)(Qb + (size_t)row * 512 + col) = EM_PK8(q0, q1); } }
;                     else if (pn < 4) { const int c = col - 512; float* ko = (samp ? out + o_ks + (size_t)(row - mp) * 512 : out + o_kp + (size_t)row * 512) + c; *(f32x4*)ko = v0; *(f32x4*)(ko + 4) = v1;
;                         if (!samp) *(u32x4*)(Kb + (size_t)row * 512 + c) = EM_PK8(v0, v1); }
;                     else if (pn < 6) { const int c = col - 1024; float* vo = (samp ? out + o_vs + (size_t)(row - mp) * 512 : out + o_vp + (size_t)row * 512) + c; *(f32x4*)vo = v0; *(f32x4*)(vo + 4) = v1;
;                         if (!samp) *(u32x4*)(Vb + (size_t)row * 512 + c) = EM_PK8(v0, v1); }
.Lp4epi_V:
	v_readlane_b32 s98, v244, 26
	v_readlane_b32 s99, v244, 27
	v_lshl_add_u32 v254, s6, 8, v1
	v_lshl_or_b32 v255, s8, 8, v163
	v_lshlrev_b32_e32 v252, 11, v254
	v_lshl_add_u32 v252, v255, 2, v252
	v_add_u32_e32 v252, 0xfffff000, v252
	v_lshlrev_b32_e32 v253, 10, v254
	v_lshl_add_u32 v253, v255, 1, v253
	v_add_u32_e32 v253, 0xfffff800, v253
	v_mov_b32_e32 v254, v252
	v_mov_b32_e32 v255, v253
	global_store_dwordx4 v254, v[126:129], s[72:73] nt
	global_store_dwordx4 v254, v[122:125], s[72:73] offset:16 nt
	v_cvt_pk_bf16_f32 v246, v126, v127
	v_cvt_pk_bf16_f32 v247, v128, v129
	v_cvt_pk_bf16_f32 v248, v122, v123
	v_cvt_pk_bf16_f32 v249, v124, v125
	global_store_dwordx4 v255, v[246:249], s[98:99]
	s_nop 1
	global_store_dwordx4 v254, v[118:121], s[72:73] offset:512 nt
	global_store_dwordx4 v254, v[114:117], s[72:73] offset:528 nt
	v_cvt_pk_bf16_f32 v246, v118, v119
	v_cvt_pk_bf16_f32 v247, v120, v121
	v_cvt_pk_bf16_f32 v248, v114, v115
	v_cvt_pk_bf16_f32 v249, v116, v117
	global_store_dwordx4 v255, v[246:249], s[98:99] offset:256
	s_nop 1
	v_add_u32_e32 v254, 0x8000, v252
	v_add_u32_e32 v255, 0x4000, v253
	global_store_dwordx4 v254, v[110:113], s[72:73] nt
	global_store_dwordx4 v254, v[106:109], s[72:73] offset:16 nt
	v_cvt_pk_bf16_f32 v246, v110, v111
	v_cvt_pk_bf16_f32 v247, v112, v113
	v_cvt_pk_bf16_f32 v248, v106, v107
	v_cvt_pk_bf16_f32 v249, v108, v109
	global_store_dwordx4 v255, v[246:249], s[98:99]
	s_nop 1
	global_store_dwordx4 v254, v[102:105], s[72:73] offset:512 nt
	global_store_dwordx4 v254, v[98:101], s[72:73] offset:528 nt
	v_cvt_pk_bf16_f32 v246, v102, v103
	v_cvt_pk_bf16_f32 v247, v104, v105
	v_cvt_pk_bf16_f32 v248, v98, v99
	v_cvt_pk_bf16_f32 v249, v100, v101
	global_store_dwordx4 v255, v[246:249], s[98:99] offset:256
	s_nop 1
	v_add_u32_e32 v254, 0x10000, v252
	v_add_u32_e32 v255, 0x8000, v253
	global_store_dwordx4 v254, v[94:97], s[72:73] nt
	global_store_dwordx4 v254, v[90:93], s[72:73] offset:16 nt
	v_cvt_pk_bf16_f32 v246, v94, v95
	v_cvt_pk_bf16_f32 v247, v96, v97
	v_cvt_pk_bf16_f32 v248, v90, v91
	v_cvt_pk_bf16_f32 v249, v92, v93
	global_store_dwordx4 v255, v[246:249], s[98:99]
	s_nop 1
	global_store_dwordx4 v254, v[86:89], s[72:73] offset:512 nt
	global_store_dwordx4 v254, v[82:85], s[72:73] offset:528 nt
	v_cvt_pk_bf16_f32 v246, v86, v87
	v_cvt_pk_bf16_f32 v247, v88, v89
	v_cvt_pk_bf16_f32 v248, v82, v83
	v_cvt_pk_bf16_f32 v249, v84, v85
	global_store_dwordx4 v255, v[246:249], s[98:99] offset:256
	s_nop 1
	v_add_u32_e32 v254, 0x18000, v252
	v_add_u32_e32 v255, 0xc000, v253
	global_store_dwordx4 v254, v[78:81], s[72:73] nt
	global_store_dwordx4 v254, v[74:77], s[72:73] offset:16 nt
	v_cvt_pk_bf16_f32 v246, v78, v79
	v_cvt_pk_bf16_f32 v247, v80, v81
	v_cvt_pk_bf16_f32 v248, v74, v75
	v_cvt_pk_bf16_f32 v249, v76, v77
	global_store_dwordx4 v255, v[246:249], s[98:99]
	s_nop 1
	global_store_dwordx4 v254, v[70:73], s[72:73] offset:512 nt
	global_store_dwordx4 v254, v[66:69], s[72:73] offset:528 nt
	v_cvt_pk_bf16_f32 v246, v70, v71
	v_cvt_pk_bf16_f32 v247, v72, v73
	v_cvt_pk_bf16_f32 v248, v66, v67
	v_cvt_pk_bf16_f32 v249, v68, v69
	global_store_dwordx4 v255, v[246:249], s[98:99] offset:256
	s_nop 1
	v_add_u32_e32 v254, 0x40000, v252
	v_add_u32_e32 v255, 0x20000, v253
	global_store_dwordx4 v254, v[62:65], s[72:73] nt
	global_store_dwordx4 v254, v[58:61], s[72:73] offset:16 nt
	v_cvt_pk_bf16_f32 v246, v62, v63
	v_cvt_pk_bf16_f32 v247, v64, v65
	v_cvt_pk_bf16_f32 v248, v58, v59
	v_cvt_pk_bf16_f32 v249, v60, v61
	global_store_dwordx4 v255, v[246:249], s[98:99]
	s_nop 1
	global_store_dwordx4 v254, v[54:57], s[72:73] offset:512 nt
	global_store_dwordx4 v254, v[50:53], s[72:73] offset:528 nt
	v_cvt_pk_bf16_f32 v246, v54, v55
	v_cvt_pk_bf16_f32 v247, v56, v57
	v_cvt_pk_bf16_f32 v248, v50, v51
	v_cvt_pk_bf16_f32 v249, v52, v53
	global_store_dwordx4 v255, v[246:249], s[98:99] offset:256
	s_nop 1
	v_add_u32_e32 v254, 0x48000, v252
	v_add_u32_e32 v255, 0x24000, v253
	global_store_dwordx4 v254, v[46:49], s[72:73] nt
	global_store_dwordx4 v254, v[42:45], s[72:73] offset:16 nt
	v_cvt_pk_bf16_f32 v246, v46, v47
	v_cvt_pk_bf16_f32 v247, v48, v49
	v_cvt_pk_bf16_f32 v248, v42, v43
	v_cvt_pk_bf16_f32 v249, v44, v45
	global_store_dwordx4 v255, v[246:249], s[98:99]
	s_nop 1
	global_store_dwordx4 v254, v[38:41], s[72:73] offset:512 nt
	global_store_dwordx4 v254, v[34:37], s[72:73] offset:528 nt
	v_cvt_pk_bf16_f32 v246, v38, v39
	v_cvt_pk_bf16_f32 v247, v40, v41
	v_cvt_pk_bf16_f32 v248, v34, v35
	v_cvt_pk_bf16_f32 v249, v36, v37
	global_store_dwordx4 v255, v[246:249], s[98:99] offset:256
	s_nop 1
	v_add_u32_e32 v254, 0x50000, v252
	v_add_u32_e32 v255, 0x28000, v253
	global_store_dwordx4 v254, v[30:33], s[72:73] nt
	global_store_dwordx4 v254, v[26:29], s[72:73] offset:16 nt
	v_cvt_pk_bf16_f32 v246, v30, v31
	v_cvt_pk_bf16_f32 v247, v32, v33
	v_cvt_pk_bf16_f32 v248, v26, v27
	v_cvt_pk_bf16_f32 v249, v28, v29
	global_store_dwordx4 v255, v[246:249], s[98:99]
	s_nop 1
	global_store_dwordx4 v254, v[22:25], s[72:73] offset:512 nt
	global_store_dwordx4 v254, v[18:21], s[72:73] offset:528 nt
	v_cvt_pk_bf16_f32 v246, v22, v23
	v_cvt_pk_bf16_f32 v247, v24, v25
	v_cvt_pk_bf16_f32 v248, v18, v19
	v_cvt_pk_bf16_f32 v249, v20, v21
	global_store_dwordx4 v255, v[246:249], s[98:99] offset:256
	s_nop 1
	v_add_u32_e32 v254, 0x58000, v252
	v_add_u32_e32 v255, 0x2c000, v253
	global_store_dwordx4 v254, v[14:17], s[72:73] nt
	global_store_dwordx4 v254, v[10:13], s[72:73] offset:16 nt
	v_cvt_pk_bf16_f32 v246, v14, v15
	v_cvt_pk_bf16_f32 v247, v16, v17
	v_cvt_pk_bf16_f32 v248, v10, v11
	v_cvt_pk_bf16_f32 v249, v12, v13
	global_store_dwordx4 v255, v[246:249], s[98:99]
	s_nop 1
	global_store_dwordx4 v254, v[6:9], s[72:73] offset:512 nt
	global_store_dwordx4 v254, v[2:5], s[72:73] offset:528 nt
	v_cvt_pk_bf16_f32 v246, v6, v7
	v_cvt_pk_bf16_f32 v247, v8, v9
	v_cvt_pk_bf16_f32 v248, v2, v3
	v_cvt_pk_bf16_f32 v249, v4, v5
	global_store_dwordx4 v255, v[246:249], s[98:99] offset:256
	s_nop 1
	s_branch .LBB0_945
